# v30 plus identity cndmask/cmp mask round-trips removed and one more phase-boundary hoist in the MLA loop
# speedup vs baseline: 1.0164x; 1.0021x over previous
.LBB0_927:
	s_add_i32 s6, s61, -1
	s_and_b32 s77, s61, 2
	s_and_b32 s79, s6, 3
	s_cmp_eq_u32 s61, 0
	s_cselect_b64 s[8:9], -1, 0
	s_mulk_i32 s79, 0x5800
	s_and_b64 s[6:7], s[8:9], exec
	s_mul_i32 s78, s77, 0x5800
	s_cselect_b32 s6, 0, s79
	s_add_i32 s76, s78, 0
	v_add_u32_e32 v199, s76, v241
	v_add_u32_e32 v210, s6, v244
	v_exp_f32_e32 v64, v64
	v_exp_f32_e32 v65, v65
	s_nop 0
	v_add_f32_e32 v84, v65, v64
	v_cvt_pk_bf16_f32 v178, v64, v65
	v_exp_f32_e32 v64, v66
	ds_read_b128 v[182:185], v199 offset:96
	ds_read_b128 v[246:249], v199 offset:128
	ds_read_b128 v[250:253], v199 offset:160
	v_exp_f32_e32 v65, v67
	v_add_f32_e32 v66, v64, v84
	s_waitcnt lgkmcnt(4)
	v_mfma_f32_32x32x16_bf16 v[80:95], v[80:83], v[122:125], 0
	v_add_f32_e32 v66, v65, v66
	v_cvt_pk_bf16_f32 v179, v64, v65
	v_mfma_f32_32x32x16_bf16 v[80:95], v[174:177], v[126:129], v[80:95]
	v_exp_f32_e32 v64, v68
	v_exp_f32_e32 v65, v69
	v_add_f32_e32 v66, v64, v66
	v_add_f32_e32 v66, v65, v66
	v_cvt_pk_bf16_f32 v180, v64, v65
	s_waitcnt lgkmcnt(3)
	v_mfma_f32_32x32x16_bf16 v[80:95], v[170:173], v[130:133], v[80:95]
	v_exp_f32_e32 v64, v70
	v_exp_f32_e32 v65, v71
	v_add_f32_e32 v66, v64, v66
	v_add_f32_e32 v170, v65, v66
	v_cvt_pk_bf16_f32 v181, v64, v65
	s_waitcnt lgkmcnt(0)
	v_mfma_f32_32x32x16_bf16 v[80:95], v[182:185], v[134:137], v[80:95]
	ds_read_b128 v[64:67], v210 offset:13376
	ds_read_b128 v[68:71], v210 offset:13408
	ds_read_b128 v[174:177], v210 offset:17984
	ds_read_b128 v[218:221], v210 offset:18016
	v_exp_f32_e32 v72, v72
	v_exp_f32_e32 v73, v73
	v_add_f32_e32 v170, v72, v170
	v_add_f32_e32 v171, v73, v170
	v_cvt_pk_bf16_f32 v170, v72, v73
	v_mfma_f32_32x32x16_bf16 v[80:95], v[246:249], v[154:157], v[80:95]
	v_exp_f32_e32 v72, v74
	v_exp_f32_e32 v73, v75
	v_add_f32_e32 v74, v72, v171
	v_add_f32_e32 v74, v73, v74
	v_cvt_pk_bf16_f32 v171, v72, v73
	v_mfma_f32_32x32x16_bf16 v[80:95], v[250:253], v[158:161], v[80:95]
	v_exp_f32_e32 v72, v76
	v_exp_f32_e32 v73, v77
	v_add_f32_e32 v74, v72, v74
	v_add_f32_e32 v74, v73, v74
	v_cvt_pk_bf16_f32 v172, v72, v73
	s_waitcnt lgkmcnt(0)
	v_mfma_f32_32x32x16_bf16 v[16:31], v[64:67], v[162:165], v[16:31]
	v_exp_f32_e32 v64, v78
	v_exp_f32_e32 v65, v79
	v_add_f32_e32 v66, v64, v74
	v_add_f32_e32 v246, v65, v66
	v_cvt_pk_bf16_f32 v173, v64, v65
	v_mfma_f32_32x32x16_bf16 v[0:15], v[174:177], v[162:165], v[0:15]
	ds_read_b128 v[64:67], v199 offset:6656
	ds_read_b128 v[182:185], v199 offset:6688
	ds_read_b128 v[174:177], v199 offset:6720
	v_cmp_ge_f32_e32 vcc, s48, v246
	s_mov_b64 s[10:11], -1
	s_mov_b64 s[6:7], -1
	v_mfma_f32_32x32x16_bf16 v[16:31], v[68:71], v[166:169], v[16:31]
	v_exp_f32_e32 v68, v80
	v_exp_f32_e32 v69, v81
	s_nop 0
	v_add_f32_e32 v70, v69, v68
	v_cvt_pk_bf16_f32 v162, v68, v69
	v_exp_f32_e32 v80, v82
	v_exp_f32_e32 v81, v83
	v_add_f32_e32 v82, v80, v70
	v_mfma_f32_32x32x16_bf16 v[0:15], v[218:221], v[166:169], v[0:15]
	s_and_saveexec_b64 s[12:13], vcc
	v_cmp_gt_f32_e32 vcc, s49, v246
	s_and_b64 s[6:7], s[8:9], vcc
	s_orn2_b64 s[6:7], s[6:7], exec
	s_or_b64 exec, exec, s[12:13]
	v_add_u32_e32 v211, s76, v243
	ds_read_b128 v[166:169], v199 offset:6752
	ds_read_b128 v[218:221], v199 offset:6784
	ds_read_b128 v[248:251], v199 offset:6816
	s_waitcnt lgkmcnt(3)
	v_mfma_f32_32x32x16_bf16 v[64:79], v[64:67], v[98:101], 0
	v_add_f32_e32 v82, v81, v82
	v_cvt_pk_bf16_f32 v163, v80, v81
	v_mfma_f32_32x32x16_bf16 v[64:79], v[182:185], v[102:105], v[64:79]
	v_exp_f32_e32 v80, v84
	v_exp_f32_e32 v81, v85
	v_add_f32_e32 v82, v80, v82
	v_add_f32_e32 v82, v81, v82
	v_cvt_pk_bf16_f32 v164, v80, v81
	v_mfma_f32_32x32x16_bf16 v[64:79], v[174:177], v[106:109], v[64:79]
	v_exp_f32_e32 v80, v86
	v_exp_f32_e32 v81, v87
	v_add_f32_e32 v82, v80, v82
	v_add_f32_e32 v174, v81, v82
	v_cvt_pk_bf16_f32 v165, v80, v81
	s_waitcnt lgkmcnt(0)
	v_mfma_f32_32x32x16_bf16 v[64:79], v[166:169], v[110:113], v[64:79]
	ds_read_b128 v[80:83], v211 offset:13312
	ds_read_b128 v[84:87], v211 offset:13344
	ds_read_b128 v[182:185], v211 offset:17920
	ds_read_b128 v[222:225], v211 offset:17952
	v_exp_f32_e32 v88, v88
	v_exp_f32_e32 v89, v89
	v_add_f32_e32 v166, v88, v174
	v_add_f32_e32 v166, v89, v166
	v_cvt_pk_bf16_f32 v174, v88, v89
	v_mfma_f32_32x32x16_bf16 v[64:79], v[218:221], v[114:117], v[64:79]
	v_exp_f32_e32 v88, v90
	v_exp_f32_e32 v89, v91
	v_add_f32_e32 v90, v88, v166
	v_add_f32_e32 v90, v89, v90
	v_cvt_pk_bf16_f32 v175, v88, v89
	v_mfma_f32_32x32x16_bf16 v[64:79], v[248:251], v[118:121], v[64:79]
	v_exp_f32_e32 v88, v92
	v_exp_f32_e32 v89, v93
	v_add_f32_e32 v90, v88, v90
	v_add_f32_e32 v90, v89, v90
	v_cvt_pk_bf16_f32 v176, v88, v89
	s_waitcnt lgkmcnt(0)
	v_mfma_f32_32x32x16_bf16 v[48:63], v[80:83], v[178:181], v[48:63]
	v_exp_f32_e32 v80, v94
	v_exp_f32_e32 v81, v95
	v_add_f32_e32 v82, v80, v90
	v_add_f32_e32 v247, v81, v82
	v_cvt_pk_bf16_f32 v177, v80, v81
	v_mfma_f32_32x32x16_bf16 v[32:47], v[182:185], v[178:181], v[32:47]
	ds_read_b128 v[80:83], v199 offset:6656
	ds_read_b128 v[182:185], v199 offset:6688
	ds_read_b128 v[178:181], v199 offset:6720
	v_cmp_ge_f32_e32 vcc, s48, v247
	v_mfma_f32_32x32x16_bf16 v[48:63], v[84:87], v[170:173], v[48:63]
	v_exp_f32_e32 v64, v64
	v_exp_f32_e32 v65, v65
	s_nop 0
	v_add_f32_e32 v84, v65, v64
	v_cvt_pk_bf16_f32 v166, v64, v65
	v_exp_f32_e32 v64, v66
	v_exp_f32_e32 v65, v67
	v_add_f32_e32 v66, v64, v84
	v_mfma_f32_32x32x16_bf16 v[32:47], v[222:225], v[170:173], v[32:47]
	s_and_saveexec_b64 s[12:13], vcc
	v_cmp_gt_f32_e32 vcc, s49, v247
	s_and_b64 s[8:9], s[8:9], vcc
	s_orn2_b64 s[10:11], s[8:9], exec
	s_or_b64 exec, exec, s[12:13]
	s_mov_b64 s[8:9], s[10:11]
	ds_read_b128 v[170:173], v199 offset:6752
	ds_read_b128 v[218:221], v199 offset:6784
	ds_read_b128 v[222:225], v199 offset:6816
	s_waitcnt lgkmcnt(3)
; #define LAS __attribute__((address_space(3)))
; template <int MODE, bool FAST> __device__ __forceinline__ bool attn_unit(LAS unsigned char* lds, const AttU& U, const int wv) {
;     ...
;     pb[1][0] = (bf16x8){0, 0, 0, 0, 0, 0, 0, 0}; pb[1][1] = pb[1][0];
;     ATT_QK(0, 0, 0);
;     bf16x8 kpre[NPRE > 0 ? NPRE : 1];
; #pragma unroll
;     for (int i_ = 0; i_ < NPRE; ++i_) kpre[i_] = *(LAS const bf16x8*)(lds + koff + i_ * 32);
	v_mfma_f32_32x32x16_bf16 v[80:95], v[80:83], v[122:125], 0
	v_add_f32_e32 v66, v65, v66
	v_cvt_pk_bf16_f32 v167, v64, v65
	v_mfma_f32_32x32x16_bf16 v[80:95], v[182:185], v[126:129], v[80:95]
	v_exp_f32_e32 v64, v68
	v_exp_f32_e32 v65, v69
	v_add_f32_e32 v66, v64, v66
	v_add_f32_e32 v66, v65, v66
	v_cvt_pk_bf16_f32 v168, v64, v65
	v_mfma_f32_32x32x16_bf16 v[80:95], v[178:181], v[130:133], v[80:95]
	v_exp_f32_e32 v64, v70
	v_exp_f32_e32 v65, v71
	v_add_f32_e32 v66, v64, v66
	v_add_f32_e32 v178, v65, v66
	v_cvt_pk_bf16_f32 v169, v64, v65
	s_waitcnt lgkmcnt(0)
	v_mfma_f32_32x32x16_bf16 v[80:95], v[170:173], v[134:137], v[80:95]
	ds_read_b128 v[64:67], v211 offset:13312
	ds_read_b128 v[68:71], v211 offset:13344
	ds_read_b128 v[182:185], v211 offset:17920
	ds_read_b128 v[248:251], v211 offset:17952
	v_exp_f32_e32 v72, v72
	v_exp_f32_e32 v73, v73
	v_add_f32_e32 v170, v72, v178
	v_add_f32_e32 v170, v73, v170
	v_cvt_pk_bf16_f32 v178, v72, v73
	v_mfma_f32_32x32x16_bf16 v[80:95], v[218:221], v[154:157], v[80:95]
	v_exp_f32_e32 v72, v74
	v_exp_f32_e32 v73, v75
	v_add_f32_e32 v74, v72, v170
	v_add_f32_e32 v74, v73, v74
	v_cvt_pk_bf16_f32 v179, v72, v73
	v_mfma_f32_32x32x16_bf16 v[80:95], v[222:225], v[158:161], v[80:95]
	v_exp_f32_e32 v72, v76
	v_exp_f32_e32 v73, v77
	v_add_f32_e32 v74, v72, v74
	v_add_f32_e32 v74, v73, v74
	v_cvt_pk_bf16_f32 v180, v72, v73
	s_waitcnt lgkmcnt(0)
	v_mfma_f32_32x32x16_bf16 v[16:31], v[64:67], v[162:165], v[16:31]
	v_exp_f32_e32 v64, v78
	v_exp_f32_e32 v65, v79
	v_add_f32_e32 v66, v64, v74
	v_add_f32_e32 v210, v65, v66
	v_cvt_pk_bf16_f32 v181, v64, v65
	v_mfma_f32_32x32x16_bf16 v[0:15], v[182:185], v[162:165], v[0:15]
	v_add_u32_e32 v226, s78, v242
	ds_read_b128 v[64:67], v226 offset:22528
	ds_read_b128 v[170:173], v226 offset:22560
	ds_read_b128 v[182:185], v226 offset:22592
	v_cmp_nge_f32_e64 s[10:11], s48, v210
	v_mfma_f32_32x32x16_bf16 v[16:31], v[68:71], v[174:177], v[16:31]
	v_exp_f32_e32 v68, v80
	v_exp_f32_e32 v69, v81
	s_nop 0
	v_add_f32_e32 v70, v69, v68
	v_cvt_pk_bf16_f32 v162, v68, v69
	v_exp_f32_e32 v80, v82
	v_exp_f32_e32 v81, v83
	v_add_f32_e32 v82, v80, v70
	v_mfma_f32_32x32x16_bf16 v[0:15], v[248:251], v[174:177], v[0:15]
	ds_read_b128 v[174:177], v226 offset:22624
	ds_read_b128 v[218:221], v226 offset:22656
	ds_read_b128 v[222:225], v226 offset:22688
	s_waitcnt lgkmcnt(3)
	v_mfma_f32_32x32x16_bf16 v[64:79], v[64:67], v[98:101], 0
	v_add_f32_e32 v82, v81, v82
	v_cvt_pk_bf16_f32 v163, v80, v81
	v_mfma_f32_32x32x16_bf16 v[64:79], v[170:173], v[102:105], v[64:79]
	v_exp_f32_e32 v80, v84
	v_exp_f32_e32 v81, v85
	v_add_f32_e32 v82, v80, v82
	v_add_f32_e32 v82, v81, v82
	v_cvt_pk_bf16_f32 v164, v80, v81
	v_mfma_f32_32x32x16_bf16 v[64:79], v[182:185], v[106:109], v[64:79]
	v_exp_f32_e32 v80, v86
	v_exp_f32_e32 v81, v87
	v_add_f32_e32 v82, v80, v82
	v_add_f32_e32 v170, v81, v82
	v_cvt_pk_bf16_f32 v165, v80, v81
	s_waitcnt lgkmcnt(0)
	v_mfma_f32_32x32x16_bf16 v[64:79], v[174:177], v[110:113], v[64:79]
	ds_read_b128 v[80:83], v211 offset:13376
	ds_read_b128 v[84:87], v211 offset:13408
	ds_read_b128 v[182:185], v211 offset:17984
	ds_read_b128 v[248:251], v211 offset:18016
	v_exp_f32_e32 v88, v88
	v_exp_f32_e32 v89, v89
	v_add_f32_e32 v170, v88, v170
	v_add_f32_e32 v171, v89, v170
	v_cvt_pk_bf16_f32 v170, v88, v89
	v_mfma_f32_32x32x16_bf16 v[64:79], v[218:221], v[114:117], v[64:79]
	v_exp_f32_e32 v88, v90
	v_exp_f32_e32 v89, v91
	v_add_f32_e32 v90, v88, v171
	v_add_f32_e32 v90, v89, v90
	v_cvt_pk_bf16_f32 v171, v88, v89
	v_mfma_f32_32x32x16_bf16 v[64:79], v[222:225], v[118:121], v[64:79]
	v_exp_f32_e32 v88, v92
	v_exp_f32_e32 v89, v93
	v_add_f32_e32 v90, v88, v90
	v_add_f32_e32 v90, v89, v90
	v_cvt_pk_bf16_f32 v172, v88, v89
	s_waitcnt lgkmcnt(0)
	v_mfma_f32_32x32x16_bf16 v[48:63], v[80:83], v[166:169], v[48:63]
	v_exp_f32_e32 v80, v94
	v_exp_f32_e32 v81, v95
	v_add_f32_e32 v82, v80, v90
	v_add_f32_e32 v211, v81, v82
	v_cvt_pk_bf16_f32 v173, v80, v81
	v_mfma_f32_32x32x16_bf16 v[32:47], v[182:185], v[166:169], v[32:47]
	ds_read_b128 v[80:83], v226 offset:22528
	ds_read_b128 v[182:185], v226 offset:22560
	ds_read_b128 v[174:177], v226 offset:22592
	v_cmp_nge_f32_e64 s[12:13], s48, v211
	v_mfma_f32_32x32x16_bf16 v[48:63], v[84:87], v[178:181], v[48:63]
	s_waitcnt lgkmcnt(0)
	s_barrier
	v_mfma_f32_32x32x16_bf16 v[32:47], v[248:251], v[178:181], v[32:47]
	s_cmpk_gt_u32 s61, 0xfc
	s_cbranch_scc1 .LBB0_933
	s_add_i32 s24, s79, 0
	v_add_u32_e32 v84, s24, v238
	v_add_u32_e32 v85, s24, v245
	v_add_u32_e32 v86, s24, v198
	s_waitcnt vmcnt(1)
	ds_write_b128 v84, v[150:153]
	s_waitcnt vmcnt(0)
	ds_write_b64 v85, v[190:191] offset:128
	ds_write_b128 v86, v[138:141] offset:13312
